# v28 + static s_setprio 1 for waves 4-7 through the FFN-in fast-path epilogue (strategy 4 applied to the epilogue)
# baseline (speedup 1.0000x reference)
; template <int MODE>
; DI void gemm_epilogue(const float* Cs, int m0, int n0, const Epi& ep) {
;     ...
;     } else if (MODE == 4) {
;         const int mt = m0 >> 7, ch0 = (n0 >> 7) * 64, c8 = (tid & 7) * 8, ch = ch0 + c8;
;         const float* cw = ep.c0;
;         const F8 w0 = ldf8(cw + ch), w1 = ldf8(cw + 2816 + ch), w2 = ldf8(cw + 2 * 2816 + ch);
;         const bool defer01 = (m0 < MP) && ((m0 & 8191) != 0);
.Lffn_fast:
	v_readfirstlane_b32 s0, v250
	s_nop 3
	s_cmpk_ge_u32 s0, 0x100
	s_cbranch_scc0 .Lffn_noprio
	s_setprio 1
